# seams after norm/mixer/combine: 4th-from-last arriver of each XCD starts an early L2 write-back
# baseline (speedup 1.0000x reference)
; DI unsigned xb_ld(unsigned* p) { return __hip_atomic_load(p, __ATOMIC_RELAXED, __HIP_MEMORY_SCOPE_AGENT); }
; DI unsigned xb_add(unsigned* p, unsigned v) { return __hip_atomic_fetch_add(p, v, __ATOMIC_RELAXED, __HIP_MEMORY_SCOPE_AGENT); }
; #define XB_SPIN(cond, bar) do { unsigned _sp = 0; while (cond) { __builtin_amdgcn_s_sleep(1); \
;     if ((++_sp & 255u) == 0u) { if (xb_ld(&(bar)[XB_TMO])) break; if (_sp > XB_SPIN_CAP) { atomicAdd(&(bar)[XB_TMO], 1u); break; } } } } while (0)
; DI void xcd_barrier(const XcdBarrier& b) {
;     ...
;     const unsigned old = xb_add(&bar[XB_XSUB(b.x)], 1u);
;     const unsigned gen = old / nloc;
;     if (old + 1u == (gen + 1u) * nloc) {
;       __builtin_amdgcn_fence(__ATOMIC_RELEASE, "agent");
;       asm volatile("s_waitcnt vmcnt(0)" ::: "memory");
;       const unsigned og = xb_add(&bar[XB_TOP], 1u);
;       const unsigned tg = og / nx;
;       if (og + 1u == (tg + 1u) * nx) xb_add(&bar[XB_TOPGEN], 1u);
;       else XB_SPIN(xb_ld(&bar[XB_TOPGEN]) == tg, bar);
;       __builtin_amdgcn_fence(__ATOMIC_ACQUIRE, "agent");
;       xb_add(&bar[XB_XGEN(b.x)], 1u);
;       asm volatile("s_waitcnt vmcnt(0)" ::: "memory");
;     } else {
;       XB_SPIN(xb_ld(&bar[XB_XGEN(b.x)]) == gen, bar);
;       __builtin_amdgcn_fence(__ATOMIC_ACQUIRE, "agent");
.LBB0_109:
	s_or_b64 exec, exec, s[2:3]
	v_cvt_f32_u32_e32 v5, v3
	s_waitcnt vmcnt(0)
	v_readfirstlane_b32 s2, v4
	v_sub_u32_e32 v4, 0, v3
	v_rcp_iflag_f32_e32 v5, v5
	v_add_u32_e32 v6, s2, v0
	v_mul_f32_e32 v5, 0x4f7ffffe, v5
	v_cvt_u32_f32_e32 v5, v5
	v_mul_lo_u32 v0, v4, v5
	v_mul_hi_u32 v0, v5, v0
	v_add_u32_e32 v0, v5, v0
	v_mul_hi_u32 v0, v6, v0
	v_mul_lo_u32 v4, v0, v3
	v_sub_u32_e32 v4, v6, v4
	v_add_u32_e32 v5, 1, v0
	v_cmp_ge_u32_e32 vcc, v4, v3
	s_nop 1
	v_cndmask_b32_e32 v0, v0, v5, vcc
	v_sub_u32_e32 v5, v4, v3
	v_cndmask_b32_e32 v4, v4, v5, vcc
	v_add_u32_e32 v5, 1, v0
	v_cmp_ge_u32_e32 vcc, v4, v3
	v_add_u32_e32 v4, 1, v6
	s_nop 0
	v_cndmask_b32_e32 v0, v0, v5, vcc
	v_mul_lo_u32 v5, v3, v0
	v_add_u32_e32 v3, v5, v3
	v_cmp_ne_u32_e32 vcc, v4, v3
	s_and_saveexec_b64 s[2:3], vcc
	s_xor_b64 s[2:3], exec, s[2:3]
	s_cbranch_execz .LBB0_123
	v_sub_u32_e32 v5, v3, v4
	s_nop 1
	v_readfirstlane_b32 s4, v5
	s_nop 0
	s_cmp_eq_u32 s4, 4
	s_cbranch_scc0 .Lewb_0
	buffer_wbl2 sc1
.Lewb_0:
	v_readlane_b32 s4, v253, 29
	v_readlane_b32 s5, v253, 30
	s_waitcnt lgkmcnt(0)
	s_nop 3
	global_load_dword v2, v1, s[4:5] sc1
	s_waitcnt vmcnt(0)
	v_cmp_eq_u32_e32 vcc, v2, v0
	s_and_saveexec_b64 s[4:5], vcc
	s_cbranch_execz .LBB0_122
	s_mov_b32 s16, 1
	s_mov_b64 s[6:7], 0
	s_branch .LBB0_113
